# even steps: y pair sum moved into the pre-swap hazard slot (one nop fewer)
# speedup vs baseline: 1.0088x; 1.0024x over previous
.LBB0_682:
	s_bitcmp1_b32 s30, 0
	s_cselect_b32 s6, 0xe000, 0
	s_add_i32 s6, s6, 0
	v_add_u32_e32 v90, s6, v58
	v_sub_u32_e32 v88, v90, v61
	v_add_u32_e32 v89, s6, v86
	ds_read_b128 v[4:7], v90 offset:0x4000
	ds_read_b128 v[8:11], v90 offset:0x0
	ds_read2st64_b32 v[108:109], v89 offset0:192 offset1:193
	ds_read2st64_b64 v[100:103], v88 offset0:64 offset1:65
	ds_read_b128 v[112:115], v90 offset:0x4200
	ds_read_b128 v[96:99], v90 offset:0x200
	ds_read_b128 v[120:123], v90 offset:0x4400
	ds_read_b128 v[124:127], v90 offset:0x400
	v_mov_b32_e32 v93, v91
	s_waitcnt lgkmcnt(5)
	v_pk_mul_f32 v[0:1], v[52:53], v[4:5] op_sel_hi:[0,1]
	v_pk_fma_f32 v[0:1], v[52:53], v[6:7], v[0:1] op_sel:[1,0,0]
	v_pk_mul_f32 v[10:11], v[108:109], v[10:11] op_sel_hi:[0,1]
	v_pk_fma_f32 v[54:55], v[52:53], v[8:9], v[10:11]
	v_add_f32_dpp v0, v0, v0 quad_perm:[1,0,3,2] row_mask:0xf bank_mask:0xf bound_ctrl:1
	s_nop 0
	ds_read_b128 v[4:7], v90 offset:0x4600
	v_add_f32_dpp v0, v0, v0 quad_perm:[2,3,0,1] row_mask:0xf bank_mask:0xf bound_ctrl:1
	s_nop 0
	ds_read_b128 v[8:11], v90 offset:0x600
	v_add_f32_dpp v0, v0, v0 row_half_mirror row_mask:0xf bank_mask:0xf bound_ctrl:1
	s_nop 0
	ds_read2st64_b32 v[110:111], v89 offset0:194 offset1:195
	ds_read2st64_b64 v[104:107], v88 offset0:66 offset1:67
	v_add_f32_dpp v2, v0, v0 row_mirror row_mask:0xf bank_mask:0xf bound_ctrl:1
	v_add_f32_dpp v0, v0, v0 row_mirror row_mask:0xf bank_mask:0xf bound_ctrl:1
	v_add_f32_dpp v1, v1, v1 quad_perm:[1,0,3,2] row_mask:0xf bank_mask:0xf bound_ctrl:1
	s_waitcnt lgkmcnt(6)
	v_permlane16_swap_b32_e32 v0, v2
	v_add_f32_e32 v0, v0, v2
	v_pk_fma_f32 v[52:53], v[100:101], v[0:1], v[54:55] op_sel_hi:[1,0,1]
	v_pk_mul_f32 v[118:119], v[52:53], v[112:113] op_sel_hi:[0,1]
	v_pk_fma_f32 v[118:119], v[52:53], v[114:115], v[118:119] op_sel:[1,0,0]
	v_pk_mul_f32 v[98:99], v[108:109], v[98:99] op_sel:[1,0]
	v_pk_fma_f32 v[54:55], v[52:53], v[96:97], v[98:99]
	v_add_f32_dpp v118, v118, v118 quad_perm:[1,0,3,2] row_mask:0xf bank_mask:0xf bound_ctrl:1
	v_add_f32_dpp v119, v119, v119 quad_perm:[1,0,3,2] row_mask:0xf bank_mask:0xf bound_ctrl:1
	s_nop 0
	ds_read_b128 v[112:115], v90 offset:0x4800
	v_add_f32_dpp v118, v118, v118 quad_perm:[2,3,0,1] row_mask:0xf bank_mask:0xf bound_ctrl:1
	s_nop 0
	ds_read_b128 v[96:99], v90 offset:0x800
	v_add_f32_dpp v118, v118, v118 row_half_mirror row_mask:0xf bank_mask:0xf bound_ctrl:1
	s_nop 0
	ds_write2_b32 v93, v1, v119 offset0:0 offset1:36
	v_add_f32_dpp v2, v118, v118 row_mirror row_mask:0xf bank_mask:0xf bound_ctrl:1
	v_add_f32_dpp v118, v118, v118 row_mirror row_mask:0xf bank_mask:0xf bound_ctrl:1
	s_nop 0
	s_waitcnt lgkmcnt(4)
	v_permlane16_swap_b32_e32 v118, v2
	v_add_f32_e32 v118, v118, v2
	v_pk_fma_f32 v[52:53], v[102:103], v[118:119], v[54:55] op_sel_hi:[1,0,1]
	v_pk_mul_f32 v[0:1], v[52:53], v[120:121] op_sel_hi:[0,1]
	v_pk_fma_f32 v[0:1], v[52:53], v[122:123], v[0:1] op_sel:[1,0,0]
	v_pk_mul_f32 v[126:127], v[110:111], v[126:127] op_sel_hi:[0,1]
	v_pk_fma_f32 v[54:55], v[52:53], v[124:125], v[126:127]
	v_add_f32_dpp v0, v0, v0 quad_perm:[1,0,3,2] row_mask:0xf bank_mask:0xf bound_ctrl:1
	s_nop 0
	ds_read_b128 v[120:123], v90 offset:0x4a00
	v_add_f32_dpp v0, v0, v0 quad_perm:[2,3,0,1] row_mask:0xf bank_mask:0xf bound_ctrl:1
	s_nop 0
	ds_read_b128 v[124:127], v90 offset:0xa00
	v_add_f32_dpp v0, v0, v0 row_half_mirror row_mask:0xf bank_mask:0xf bound_ctrl:1
	s_nop 0
	ds_read2st64_b32 v[108:109], v89 offset0:196 offset1:197
	ds_read2st64_b64 v[100:103], v88 offset0:68 offset1:69
	v_add_f32_dpp v2, v0, v0 row_mirror row_mask:0xf bank_mask:0xf bound_ctrl:1
	v_add_f32_dpp v0, v0, v0 row_mirror row_mask:0xf bank_mask:0xf bound_ctrl:1
	v_add_f32_dpp v1, v1, v1 quad_perm:[1,0,3,2] row_mask:0xf bank_mask:0xf bound_ctrl:1
	s_waitcnt lgkmcnt(7)
	v_permlane16_swap_b32_e32 v0, v2
	v_add_f32_e32 v0, v0, v2
	v_pk_fma_f32 v[52:53], v[104:105], v[0:1], v[54:55] op_sel_hi:[1,0,1]
	v_pk_mul_f32 v[118:119], v[52:53], v[4:5] op_sel_hi:[0,1]
	v_pk_fma_f32 v[118:119], v[52:53], v[6:7], v[118:119] op_sel:[1,0,0]
	v_pk_mul_f32 v[10:11], v[110:111], v[10:11] op_sel:[1,0]
	v_pk_fma_f32 v[54:55], v[52:53], v[8:9], v[10:11]
	v_add_f32_dpp v118, v118, v118 quad_perm:[1,0,3,2] row_mask:0xf bank_mask:0xf bound_ctrl:1
	v_add_f32_dpp v119, v119, v119 quad_perm:[1,0,3,2] row_mask:0xf bank_mask:0xf bound_ctrl:1
	s_nop 0
	ds_read_b128 v[4:7], v90 offset:0x4c00
	v_add_f32_dpp v118, v118, v118 quad_perm:[2,3,0,1] row_mask:0xf bank_mask:0xf bound_ctrl:1
	s_nop 0
	ds_read_b128 v[8:11], v90 offset:0xc00
	v_add_f32_dpp v118, v118, v118 row_half_mirror row_mask:0xf bank_mask:0xf bound_ctrl:1
	s_nop 0
	ds_write2_b32 v93, v1, v119 offset0:72 offset1:108
	v_add_f32_dpp v2, v118, v118 row_mirror row_mask:0xf bank_mask:0xf bound_ctrl:1
	v_add_f32_dpp v118, v118, v118 row_mirror row_mask:0xf bank_mask:0xf bound_ctrl:1
	s_nop 0
	s_waitcnt lgkmcnt(4)
	v_permlane16_swap_b32_e32 v118, v2
	v_add_f32_e32 v118, v118, v2
	v_pk_fma_f32 v[52:53], v[106:107], v[118:119], v[54:55] op_sel_hi:[1,0,1]
	v_pk_mul_f32 v[0:1], v[52:53], v[112:113] op_sel_hi:[0,1]
	v_pk_fma_f32 v[0:1], v[52:53], v[114:115], v[0:1] op_sel:[1,0,0]
	v_pk_mul_f32 v[98:99], v[108:109], v[98:99] op_sel_hi:[0,1]
	v_pk_fma_f32 v[54:55], v[52:53], v[96:97], v[98:99]
	v_add_f32_dpp v0, v0, v0 quad_perm:[1,0,3,2] row_mask:0xf bank_mask:0xf bound_ctrl:1
	s_nop 0
	ds_read_b128 v[112:115], v90 offset:0x4e00
	v_add_f32_dpp v0, v0, v0 quad_perm:[2,3,0,1] row_mask:0xf bank_mask:0xf bound_ctrl:1
	s_nop 0
	ds_read_b128 v[96:99], v90 offset:0xe00
	v_add_f32_dpp v0, v0, v0 row_half_mirror row_mask:0xf bank_mask:0xf bound_ctrl:1
	s_nop 0
	ds_read2st64_b32 v[110:111], v89 offset0:198 offset1:199
	ds_read2st64_b64 v[104:107], v88 offset0:70 offset1:71
	v_add_f32_dpp v2, v0, v0 row_mirror row_mask:0xf bank_mask:0xf bound_ctrl:1
	v_add_f32_dpp v0, v0, v0 row_mirror row_mask:0xf bank_mask:0xf bound_ctrl:1
	v_add_f32_dpp v1, v1, v1 quad_perm:[1,0,3,2] row_mask:0xf bank_mask:0xf bound_ctrl:1
	s_waitcnt lgkmcnt(7)
	v_permlane16_swap_b32_e32 v0, v2
	v_add_f32_e32 v0, v0, v2
	v_pk_fma_f32 v[52:53], v[100:101], v[0:1], v[54:55] op_sel_hi:[1,0,1]
	v_pk_mul_f32 v[118:119], v[52:53], v[120:121] op_sel_hi:[0,1]
	v_pk_fma_f32 v[118:119], v[52:53], v[122:123], v[118:119] op_sel:[1,0,0]
	v_pk_mul_f32 v[126:127], v[108:109], v[126:127] op_sel:[1,0]
	v_pk_fma_f32 v[54:55], v[52:53], v[124:125], v[126:127]
	v_add_f32_dpp v118, v118, v118 quad_perm:[1,0,3,2] row_mask:0xf bank_mask:0xf bound_ctrl:1
	v_add_f32_dpp v119, v119, v119 quad_perm:[1,0,3,2] row_mask:0xf bank_mask:0xf bound_ctrl:1
	s_nop 0
	ds_read_b128 v[120:123], v90 offset:0x5000
	v_add_f32_dpp v118, v118, v118 quad_perm:[2,3,0,1] row_mask:0xf bank_mask:0xf bound_ctrl:1
	s_nop 0
	ds_read_b128 v[124:127], v90 offset:0x1000
	v_add_f32_dpp v118, v118, v118 row_half_mirror row_mask:0xf bank_mask:0xf bound_ctrl:1
	s_nop 0
	ds_write2_b32 v93, v1, v119 offset0:144 offset1:180
	v_add_f32_dpp v2, v118, v118 row_mirror row_mask:0xf bank_mask:0xf bound_ctrl:1
	v_add_f32_dpp v118, v118, v118 row_mirror row_mask:0xf bank_mask:0xf bound_ctrl:1
	s_nop 0
	s_waitcnt lgkmcnt(4)
	v_permlane16_swap_b32_e32 v118, v2
	v_add_f32_e32 v118, v118, v2
	v_pk_fma_f32 v[52:53], v[102:103], v[118:119], v[54:55] op_sel_hi:[1,0,1]
	v_pk_mul_f32 v[0:1], v[52:53], v[4:5] op_sel_hi:[0,1]
	v_pk_fma_f32 v[0:1], v[52:53], v[6:7], v[0:1] op_sel:[1,0,0]
	v_pk_mul_f32 v[10:11], v[110:111], v[10:11] op_sel_hi:[0,1]
	v_pk_fma_f32 v[54:55], v[52:53], v[8:9], v[10:11]
	v_add_f32_dpp v0, v0, v0 quad_perm:[1,0,3,2] row_mask:0xf bank_mask:0xf bound_ctrl:1
	s_nop 0
	ds_read_b128 v[4:7], v90 offset:0x5200
	v_add_f32_dpp v0, v0, v0 quad_perm:[2,3,0,1] row_mask:0xf bank_mask:0xf bound_ctrl:1
	s_nop 0
	ds_read_b128 v[8:11], v90 offset:0x1200
	v_add_f32_dpp v0, v0, v0 row_half_mirror row_mask:0xf bank_mask:0xf bound_ctrl:1
	s_nop 0
	ds_read2st64_b32 v[108:109], v89 offset0:200 offset1:201
	ds_read2st64_b64 v[100:103], v88 offset0:72 offset1:73
	v_add_f32_dpp v2, v0, v0 row_mirror row_mask:0xf bank_mask:0xf bound_ctrl:1
	v_add_f32_dpp v0, v0, v0 row_mirror row_mask:0xf bank_mask:0xf bound_ctrl:1
	v_add_f32_dpp v1, v1, v1 quad_perm:[1,0,3,2] row_mask:0xf bank_mask:0xf bound_ctrl:1
	s_waitcnt lgkmcnt(7)
	v_permlane16_swap_b32_e32 v0, v2
	v_add_f32_e32 v0, v0, v2
	v_pk_fma_f32 v[52:53], v[104:105], v[0:1], v[54:55] op_sel_hi:[1,0,1]
	v_pk_mul_f32 v[118:119], v[52:53], v[112:113] op_sel_hi:[0,1]
	v_pk_fma_f32 v[118:119], v[52:53], v[114:115], v[118:119] op_sel:[1,0,0]
	v_pk_mul_f32 v[98:99], v[110:111], v[98:99] op_sel:[1,0]
	v_pk_fma_f32 v[54:55], v[52:53], v[96:97], v[98:99]
	v_add_f32_dpp v118, v118, v118 quad_perm:[1,0,3,2] row_mask:0xf bank_mask:0xf bound_ctrl:1
	v_add_f32_dpp v119, v119, v119 quad_perm:[1,0,3,2] row_mask:0xf bank_mask:0xf bound_ctrl:1
	s_nop 0
	ds_read_b128 v[112:115], v90 offset:0x5400
	v_add_f32_dpp v118, v118, v118 quad_perm:[2,3,0,1] row_mask:0xf bank_mask:0xf bound_ctrl:1
	s_nop 0
	ds_read_b128 v[96:99], v90 offset:0x1400
	v_add_f32_dpp v118, v118, v118 row_half_mirror row_mask:0xf bank_mask:0xf bound_ctrl:1
	s_nop 0
	ds_write2_b32 v93, v1, v119 offset0:216 offset1:252
	v_add_f32_dpp v2, v118, v118 row_mirror row_mask:0xf bank_mask:0xf bound_ctrl:1
	v_add_f32_dpp v118, v118, v118 row_mirror row_mask:0xf bank_mask:0xf bound_ctrl:1
	s_nop 0
	s_waitcnt lgkmcnt(4)
	v_permlane16_swap_b32_e32 v118, v2
	v_add_f32_e32 v118, v118, v2
	v_pk_fma_f32 v[52:53], v[106:107], v[118:119], v[54:55] op_sel_hi:[1,0,1]
	v_pk_mul_f32 v[0:1], v[52:53], v[120:121] op_sel_hi:[0,1]
	v_pk_fma_f32 v[0:1], v[52:53], v[122:123], v[0:1] op_sel:[1,0,0]
	v_pk_mul_f32 v[126:127], v[108:109], v[126:127] op_sel_hi:[0,1]
	v_pk_fma_f32 v[54:55], v[52:53], v[124:125], v[126:127]
	v_add_f32_dpp v0, v0, v0 quad_perm:[1,0,3,2] row_mask:0xf bank_mask:0xf bound_ctrl:1
	v_add_u32_e32 v93, 0x480, v93
	ds_read_b128 v[120:123], v90 offset:0x5600
	v_add_f32_dpp v0, v0, v0 quad_perm:[2,3,0,1] row_mask:0xf bank_mask:0xf bound_ctrl:1
	s_nop 0
	ds_read_b128 v[124:127], v90 offset:0x1600
	v_add_f32_dpp v0, v0, v0 row_half_mirror row_mask:0xf bank_mask:0xf bound_ctrl:1
	s_nop 0
	ds_read2st64_b32 v[110:111], v89 offset0:202 offset1:203
	ds_read2st64_b64 v[104:107], v88 offset0:74 offset1:75
	v_add_f32_dpp v2, v0, v0 row_mirror row_mask:0xf bank_mask:0xf bound_ctrl:1
	v_add_f32_dpp v0, v0, v0 row_mirror row_mask:0xf bank_mask:0xf bound_ctrl:1
	v_add_f32_dpp v1, v1, v1 quad_perm:[1,0,3,2] row_mask:0xf bank_mask:0xf bound_ctrl:1
	s_waitcnt lgkmcnt(7)
	v_permlane16_swap_b32_e32 v0, v2
	v_add_f32_e32 v0, v0, v2
	v_pk_fma_f32 v[52:53], v[100:101], v[0:1], v[54:55] op_sel_hi:[1,0,1]
	v_pk_mul_f32 v[118:119], v[52:53], v[4:5] op_sel_hi:[0,1]
	v_pk_fma_f32 v[118:119], v[52:53], v[6:7], v[118:119] op_sel:[1,0,0]
	v_pk_mul_f32 v[10:11], v[108:109], v[10:11] op_sel:[1,0]
	v_pk_fma_f32 v[54:55], v[52:53], v[8:9], v[10:11]
	v_add_f32_dpp v118, v118, v118 quad_perm:[1,0,3,2] row_mask:0xf bank_mask:0xf bound_ctrl:1
	v_add_f32_dpp v119, v119, v119 quad_perm:[1,0,3,2] row_mask:0xf bank_mask:0xf bound_ctrl:1
	s_nop 0
	ds_read_b128 v[4:7], v90 offset:0x5800
	v_add_f32_dpp v118, v118, v118 quad_perm:[2,3,0,1] row_mask:0xf bank_mask:0xf bound_ctrl:1
	s_nop 0
	ds_read_b128 v[8:11], v90 offset:0x1800
	v_add_f32_dpp v118, v118, v118 row_half_mirror row_mask:0xf bank_mask:0xf bound_ctrl:1
	s_nop 0
	ds_write2_b32 v93, v1, v119 offset0:0 offset1:36
	v_add_f32_dpp v2, v118, v118 row_mirror row_mask:0xf bank_mask:0xf bound_ctrl:1
	v_add_f32_dpp v118, v118, v118 row_mirror row_mask:0xf bank_mask:0xf bound_ctrl:1
	s_nop 0
	s_waitcnt lgkmcnt(4)
	v_permlane16_swap_b32_e32 v118, v2
	v_add_f32_e32 v118, v118, v2
	v_pk_fma_f32 v[52:53], v[102:103], v[118:119], v[54:55] op_sel_hi:[1,0,1]
	v_pk_mul_f32 v[0:1], v[52:53], v[112:113] op_sel_hi:[0,1]
	v_pk_fma_f32 v[0:1], v[52:53], v[114:115], v[0:1] op_sel:[1,0,0]
	v_pk_mul_f32 v[98:99], v[110:111], v[98:99] op_sel_hi:[0,1]
	v_pk_fma_f32 v[54:55], v[52:53], v[96:97], v[98:99]
	v_add_f32_dpp v0, v0, v0 quad_perm:[1,0,3,2] row_mask:0xf bank_mask:0xf bound_ctrl:1
	s_nop 0
	ds_read_b128 v[112:115], v90 offset:0x5a00
	v_add_f32_dpp v0, v0, v0 quad_perm:[2,3,0,1] row_mask:0xf bank_mask:0xf bound_ctrl:1
	s_nop 0
	ds_read_b128 v[96:99], v90 offset:0x1a00
	v_add_f32_dpp v0, v0, v0 row_half_mirror row_mask:0xf bank_mask:0xf bound_ctrl:1
	s_nop 0
	ds_read2st64_b32 v[108:109], v89 offset0:204 offset1:205
	ds_read2st64_b64 v[100:103], v88 offset0:76 offset1:77
	v_add_f32_dpp v2, v0, v0 row_mirror row_mask:0xf bank_mask:0xf bound_ctrl:1
	v_add_f32_dpp v0, v0, v0 row_mirror row_mask:0xf bank_mask:0xf bound_ctrl:1
	v_add_f32_dpp v1, v1, v1 quad_perm:[1,0,3,2] row_mask:0xf bank_mask:0xf bound_ctrl:1
	s_waitcnt lgkmcnt(7)
	v_permlane16_swap_b32_e32 v0, v2
	v_add_f32_e32 v0, v0, v2
	v_pk_fma_f32 v[52:53], v[104:105], v[0:1], v[54:55] op_sel_hi:[1,0,1]
	v_pk_mul_f32 v[118:119], v[52:53], v[120:121] op_sel_hi:[0,1]
	v_pk_fma_f32 v[118:119], v[52:53], v[122:123], v[118:119] op_sel:[1,0,0]
	v_pk_mul_f32 v[126:127], v[110:111], v[126:127] op_sel:[1,0]
	v_pk_fma_f32 v[54:55], v[52:53], v[124:125], v[126:127]
	v_add_f32_dpp v118, v118, v118 quad_perm:[1,0,3,2] row_mask:0xf bank_mask:0xf bound_ctrl:1
	v_add_f32_dpp v119, v119, v119 quad_perm:[1,0,3,2] row_mask:0xf bank_mask:0xf bound_ctrl:1
	s_nop 0
	ds_read_b128 v[120:123], v90 offset:0x5c00
	v_add_f32_dpp v118, v118, v118 quad_perm:[2,3,0,1] row_mask:0xf bank_mask:0xf bound_ctrl:1
	s_nop 0
	ds_read_b128 v[124:127], v90 offset:0x1c00
	v_add_f32_dpp v118, v118, v118 row_half_mirror row_mask:0xf bank_mask:0xf bound_ctrl:1
	s_nop 0
	ds_write2_b32 v93, v1, v119 offset0:72 offset1:108
	v_add_f32_dpp v2, v118, v118 row_mirror row_mask:0xf bank_mask:0xf bound_ctrl:1
	v_add_f32_dpp v118, v118, v118 row_mirror row_mask:0xf bank_mask:0xf bound_ctrl:1
	s_nop 0
	s_waitcnt lgkmcnt(4)
	v_permlane16_swap_b32_e32 v118, v2
	v_add_f32_e32 v118, v118, v2
	v_pk_fma_f32 v[52:53], v[106:107], v[118:119], v[54:55] op_sel_hi:[1,0,1]
	v_pk_mul_f32 v[0:1], v[52:53], v[4:5] op_sel_hi:[0,1]
	v_pk_fma_f32 v[0:1], v[52:53], v[6:7], v[0:1] op_sel:[1,0,0]
	v_pk_mul_f32 v[10:11], v[108:109], v[10:11] op_sel_hi:[0,1]
	v_pk_fma_f32 v[54:55], v[52:53], v[8:9], v[10:11]
	v_add_f32_dpp v0, v0, v0 quad_perm:[1,0,3,2] row_mask:0xf bank_mask:0xf bound_ctrl:1
	s_nop 0
	ds_read_b128 v[4:7], v90 offset:0x5e00
	v_add_f32_dpp v0, v0, v0 quad_perm:[2,3,0,1] row_mask:0xf bank_mask:0xf bound_ctrl:1
	s_nop 0
	ds_read_b128 v[8:11], v90 offset:0x1e00
	v_add_f32_dpp v0, v0, v0 row_half_mirror row_mask:0xf bank_mask:0xf bound_ctrl:1
	s_nop 0
	ds_read2st64_b32 v[110:111], v89 offset0:206 offset1:207
	ds_read2st64_b64 v[104:107], v88 offset0:78 offset1:79
	v_add_f32_dpp v2, v0, v0 row_mirror row_mask:0xf bank_mask:0xf bound_ctrl:1
	v_add_f32_dpp v0, v0, v0 row_mirror row_mask:0xf bank_mask:0xf bound_ctrl:1
	v_add_f32_dpp v1, v1, v1 quad_perm:[1,0,3,2] row_mask:0xf bank_mask:0xf bound_ctrl:1
	s_waitcnt lgkmcnt(7)
	v_permlane16_swap_b32_e32 v0, v2
	v_add_f32_e32 v0, v0, v2
	v_pk_fma_f32 v[52:53], v[100:101], v[0:1], v[54:55] op_sel_hi:[1,0,1]
	v_pk_mul_f32 v[118:119], v[52:53], v[112:113] op_sel_hi:[0,1]
	v_pk_fma_f32 v[118:119], v[52:53], v[114:115], v[118:119] op_sel:[1,0,0]
	v_pk_mul_f32 v[98:99], v[108:109], v[98:99] op_sel:[1,0]
	v_pk_fma_f32 v[54:55], v[52:53], v[96:97], v[98:99]
	v_add_f32_dpp v118, v118, v118 quad_perm:[1,0,3,2] row_mask:0xf bank_mask:0xf bound_ctrl:1
	v_add_f32_dpp v119, v119, v119 quad_perm:[1,0,3,2] row_mask:0xf bank_mask:0xf bound_ctrl:1
	s_nop 0
	ds_read_b128 v[112:115], v90 offset:0x6000
	v_add_f32_dpp v118, v118, v118 quad_perm:[2,3,0,1] row_mask:0xf bank_mask:0xf bound_ctrl:1
	s_nop 0
	ds_read_b128 v[96:99], v90 offset:0x2000
	v_add_f32_dpp v118, v118, v118 row_half_mirror row_mask:0xf bank_mask:0xf bound_ctrl:1
	s_nop 0
	ds_write2_b32 v93, v1, v119 offset0:144 offset1:180
	v_add_f32_dpp v2, v118, v118 row_mirror row_mask:0xf bank_mask:0xf bound_ctrl:1
	v_add_f32_dpp v118, v118, v118 row_mirror row_mask:0xf bank_mask:0xf bound_ctrl:1
	s_nop 0
	s_waitcnt lgkmcnt(4)
	v_permlane16_swap_b32_e32 v118, v2
	v_add_f32_e32 v118, v118, v2
	v_pk_fma_f32 v[52:53], v[102:103], v[118:119], v[54:55] op_sel_hi:[1,0,1]
	v_pk_mul_f32 v[0:1], v[52:53], v[120:121] op_sel_hi:[0,1]
	v_pk_fma_f32 v[0:1], v[52:53], v[122:123], v[0:1] op_sel:[1,0,0]
	v_pk_mul_f32 v[126:127], v[110:111], v[126:127] op_sel_hi:[0,1]
	v_pk_fma_f32 v[54:55], v[52:53], v[124:125], v[126:127]
	v_add_f32_dpp v0, v0, v0 quad_perm:[1,0,3,2] row_mask:0xf bank_mask:0xf bound_ctrl:1
	s_nop 0
	ds_read_b128 v[120:123], v90 offset:0x6200
	v_add_f32_dpp v0, v0, v0 quad_perm:[2,3,0,1] row_mask:0xf bank_mask:0xf bound_ctrl:1
	s_nop 0
	ds_read_b128 v[124:127], v90 offset:0x2200
	v_add_f32_dpp v0, v0, v0 row_half_mirror row_mask:0xf bank_mask:0xf bound_ctrl:1
	s_nop 0
	ds_read2st64_b32 v[108:109], v89 offset0:208 offset1:209
	ds_read2st64_b64 v[100:103], v88 offset0:80 offset1:81
	v_add_f32_dpp v2, v0, v0 row_mirror row_mask:0xf bank_mask:0xf bound_ctrl:1
	v_add_f32_dpp v0, v0, v0 row_mirror row_mask:0xf bank_mask:0xf bound_ctrl:1
	v_add_f32_dpp v1, v1, v1 quad_perm:[1,0,3,2] row_mask:0xf bank_mask:0xf bound_ctrl:1
	s_waitcnt lgkmcnt(7)
	v_permlane16_swap_b32_e32 v0, v2
	v_add_f32_e32 v0, v0, v2
	v_pk_fma_f32 v[52:53], v[104:105], v[0:1], v[54:55] op_sel_hi:[1,0,1]
	v_pk_mul_f32 v[118:119], v[52:53], v[4:5] op_sel_hi:[0,1]
	v_pk_fma_f32 v[118:119], v[52:53], v[6:7], v[118:119] op_sel:[1,0,0]
	v_pk_mul_f32 v[10:11], v[110:111], v[10:11] op_sel:[1,0]
	v_pk_fma_f32 v[54:55], v[52:53], v[8:9], v[10:11]
	v_add_f32_dpp v118, v118, v118 quad_perm:[1,0,3,2] row_mask:0xf bank_mask:0xf bound_ctrl:1
	v_add_f32_dpp v119, v119, v119 quad_perm:[1,0,3,2] row_mask:0xf bank_mask:0xf bound_ctrl:1
	s_nop 0
	ds_read_b128 v[4:7], v90 offset:0x6400
	v_add_f32_dpp v118, v118, v118 quad_perm:[2,3,0,1] row_mask:0xf bank_mask:0xf bound_ctrl:1
	s_nop 0
	ds_read_b128 v[8:11], v90 offset:0x2400
	v_add_f32_dpp v118, v118, v118 row_half_mirror row_mask:0xf bank_mask:0xf bound_ctrl:1
	s_nop 0
	ds_write2_b32 v93, v1, v119 offset0:216 offset1:252
	v_add_f32_dpp v2, v118, v118 row_mirror row_mask:0xf bank_mask:0xf bound_ctrl:1
	v_add_f32_dpp v118, v118, v118 row_mirror row_mask:0xf bank_mask:0xf bound_ctrl:1
	s_nop 0
	s_waitcnt lgkmcnt(4)
	v_permlane16_swap_b32_e32 v118, v2
	v_add_f32_e32 v118, v118, v2
	v_pk_fma_f32 v[52:53], v[106:107], v[118:119], v[54:55] op_sel_hi:[1,0,1]
	s_cmp_eq_u32 s88, 0x800000
	s_cbranch_scc1 .LBB0_684
	v_pk_mul_f32 v[0:1], v[52:53], v[112:113] op_sel_hi:[0,1]
	v_pk_fma_f32 v[0:1], v[52:53], v[114:115], v[0:1] op_sel:[1,0,0]
	v_pk_mul_f32 v[98:99], v[108:109], v[98:99] op_sel_hi:[0,1]
	v_pk_fma_f32 v[54:55], v[52:53], v[96:97], v[98:99]
	v_add_f32_dpp v0, v0, v0 quad_perm:[1,0,3,2] row_mask:0xf bank_mask:0xf bound_ctrl:1
	v_add_u32_e32 v93, 0x480, v93
	ds_read_b128 v[112:115], v90 offset:0x6600
	v_add_f32_dpp v0, v0, v0 quad_perm:[2,3,0,1] row_mask:0xf bank_mask:0xf bound_ctrl:1
	s_nop 0
	ds_read_b128 v[96:99], v90 offset:0x2600
	v_add_f32_dpp v0, v0, v0 row_half_mirror row_mask:0xf bank_mask:0xf bound_ctrl:1
	s_nop 0
	ds_read2st64_b32 v[110:111], v89 offset0:210 offset1:211
	ds_read2st64_b64 v[104:107], v88 offset0:82 offset1:83
	v_add_f32_dpp v2, v0, v0 row_mirror row_mask:0xf bank_mask:0xf bound_ctrl:1
	v_add_f32_dpp v0, v0, v0 row_mirror row_mask:0xf bank_mask:0xf bound_ctrl:1
	v_add_f32_dpp v1, v1, v1 quad_perm:[1,0,3,2] row_mask:0xf bank_mask:0xf bound_ctrl:1
	s_waitcnt lgkmcnt(7)
	v_permlane16_swap_b32_e32 v0, v2
	v_add_f32_e32 v0, v0, v2
	v_pk_fma_f32 v[52:53], v[100:101], v[0:1], v[54:55] op_sel_hi:[1,0,1]
	v_pk_mul_f32 v[118:119], v[52:53], v[120:121] op_sel_hi:[0,1]
	v_pk_fma_f32 v[118:119], v[52:53], v[122:123], v[118:119] op_sel:[1,0,0]
	v_pk_mul_f32 v[126:127], v[108:109], v[126:127] op_sel:[1,0]
	v_pk_fma_f32 v[54:55], v[52:53], v[124:125], v[126:127]
	v_add_f32_dpp v118, v118, v118 quad_perm:[1,0,3,2] row_mask:0xf bank_mask:0xf bound_ctrl:1
	v_add_f32_dpp v119, v119, v119 quad_perm:[1,0,3,2] row_mask:0xf bank_mask:0xf bound_ctrl:1
	s_nop 0
	ds_read_b128 v[120:123], v90 offset:0x6800
	v_add_f32_dpp v118, v118, v118 quad_perm:[2,3,0,1] row_mask:0xf bank_mask:0xf bound_ctrl:1
	s_nop 0
	ds_read_b128 v[124:127], v90 offset:0x2800
	v_add_f32_dpp v118, v118, v118 row_half_mirror row_mask:0xf bank_mask:0xf bound_ctrl:1
	s_nop 0
	ds_write2_b32 v93, v1, v119 offset0:0 offset1:36
	v_add_f32_dpp v2, v118, v118 row_mirror row_mask:0xf bank_mask:0xf bound_ctrl:1
	v_add_f32_dpp v118, v118, v118 row_mirror row_mask:0xf bank_mask:0xf bound_ctrl:1
	s_nop 0
	s_waitcnt lgkmcnt(4)
	v_permlane16_swap_b32_e32 v118, v2
	v_add_f32_e32 v118, v118, v2
	v_pk_fma_f32 v[52:53], v[102:103], v[118:119], v[54:55] op_sel_hi:[1,0,1]
	v_pk_mul_f32 v[0:1], v[52:53], v[4:5] op_sel_hi:[0,1]
	v_pk_fma_f32 v[0:1], v[52:53], v[6:7], v[0:1] op_sel:[1,0,0]
	v_pk_mul_f32 v[10:11], v[110:111], v[10:11] op_sel_hi:[0,1]
	v_pk_fma_f32 v[54:55], v[52:53], v[8:9], v[10:11]
	v_add_f32_dpp v0, v0, v0 quad_perm:[1,0,3,2] row_mask:0xf bank_mask:0xf bound_ctrl:1
	s_nop 0
	ds_read_b128 v[4:7], v90 offset:0x6a00
	v_add_f32_dpp v0, v0, v0 quad_perm:[2,3,0,1] row_mask:0xf bank_mask:0xf bound_ctrl:1
	s_nop 0
	ds_read_b128 v[8:11], v90 offset:0x2a00
	v_add_f32_dpp v0, v0, v0 row_half_mirror row_mask:0xf bank_mask:0xf bound_ctrl:1
	s_nop 0
	ds_read2st64_b32 v[108:109], v89 offset0:212 offset1:213
	ds_read2st64_b64 v[100:103], v88 offset0:84 offset1:85
	v_add_f32_dpp v2, v0, v0 row_mirror row_mask:0xf bank_mask:0xf bound_ctrl:1
	v_add_f32_dpp v0, v0, v0 row_mirror row_mask:0xf bank_mask:0xf bound_ctrl:1
	v_add_f32_dpp v1, v1, v1 quad_perm:[1,0,3,2] row_mask:0xf bank_mask:0xf bound_ctrl:1
	s_waitcnt lgkmcnt(7)
	v_permlane16_swap_b32_e32 v0, v2
	v_add_f32_e32 v0, v0, v2
	v_pk_fma_f32 v[52:53], v[104:105], v[0:1], v[54:55] op_sel_hi:[1,0,1]
	v_pk_mul_f32 v[118:119], v[52:53], v[112:113] op_sel_hi:[0,1]
	v_pk_fma_f32 v[118:119], v[52:53], v[114:115], v[118:119] op_sel:[1,0,0]
	v_pk_mul_f32 v[98:99], v[110:111], v[98:99] op_sel:[1,0]
	v_pk_fma_f32 v[54:55], v[52:53], v[96:97], v[98:99]
	v_add_f32_dpp v118, v118, v118 quad_perm:[1,0,3,2] row_mask:0xf bank_mask:0xf bound_ctrl:1
	v_add_f32_dpp v119, v119, v119 quad_perm:[1,0,3,2] row_mask:0xf bank_mask:0xf bound_ctrl:1
	s_nop 0
	ds_read_b128 v[112:115], v90 offset:0x6c00
	v_add_f32_dpp v118, v118, v118 quad_perm:[2,3,0,1] row_mask:0xf bank_mask:0xf bound_ctrl:1
	s_nop 0
	ds_read_b128 v[96:99], v90 offset:0x2c00
	v_add_f32_dpp v118, v118, v118 row_half_mirror row_mask:0xf bank_mask:0xf bound_ctrl:1
	s_nop 0
	ds_write2_b32 v93, v1, v119 offset0:72 offset1:108
	v_add_f32_dpp v2, v118, v118 row_mirror row_mask:0xf bank_mask:0xf bound_ctrl:1
	v_add_f32_dpp v118, v118, v118 row_mirror row_mask:0xf bank_mask:0xf bound_ctrl:1
	s_nop 0
	s_waitcnt lgkmcnt(4)
	v_permlane16_swap_b32_e32 v118, v2
	v_add_f32_e32 v118, v118, v2
	v_pk_fma_f32 v[52:53], v[106:107], v[118:119], v[54:55] op_sel_hi:[1,0,1]
	v_pk_mul_f32 v[0:1], v[52:53], v[120:121] op_sel_hi:[0,1]
	v_pk_fma_f32 v[0:1], v[52:53], v[122:123], v[0:1] op_sel:[1,0,0]
	v_pk_mul_f32 v[126:127], v[108:109], v[126:127] op_sel_hi:[0,1]
	v_pk_fma_f32 v[54:55], v[52:53], v[124:125], v[126:127]
	v_add_f32_dpp v0, v0, v0 quad_perm:[1,0,3,2] row_mask:0xf bank_mask:0xf bound_ctrl:1
	s_nop 0
	ds_read_b128 v[120:123], v90 offset:0x6e00
	v_add_f32_dpp v0, v0, v0 quad_perm:[2,3,0,1] row_mask:0xf bank_mask:0xf bound_ctrl:1
	s_nop 0
	ds_read_b128 v[124:127], v90 offset:0x2e00
	v_add_f32_dpp v0, v0, v0 row_half_mirror row_mask:0xf bank_mask:0xf bound_ctrl:1
	s_nop 0
	ds_read2st64_b32 v[110:111], v89 offset0:214 offset1:215
	ds_read2st64_b64 v[104:107], v88 offset0:86 offset1:87
	v_add_f32_dpp v2, v0, v0 row_mirror row_mask:0xf bank_mask:0xf bound_ctrl:1
	v_add_f32_dpp v0, v0, v0 row_mirror row_mask:0xf bank_mask:0xf bound_ctrl:1
	v_add_f32_dpp v1, v1, v1 quad_perm:[1,0,3,2] row_mask:0xf bank_mask:0xf bound_ctrl:1
	s_waitcnt lgkmcnt(7)
	v_permlane16_swap_b32_e32 v0, v2
	v_add_f32_e32 v0, v0, v2
	v_pk_fma_f32 v[52:53], v[100:101], v[0:1], v[54:55] op_sel_hi:[1,0,1]
	v_pk_mul_f32 v[118:119], v[52:53], v[4:5] op_sel_hi:[0,1]
	v_pk_fma_f32 v[118:119], v[52:53], v[6:7], v[118:119] op_sel:[1,0,0]
	v_pk_mul_f32 v[10:11], v[108:109], v[10:11] op_sel:[1,0]
	v_pk_fma_f32 v[54:55], v[52:53], v[8:9], v[10:11]
	v_add_f32_dpp v118, v118, v118 quad_perm:[1,0,3,2] row_mask:0xf bank_mask:0xf bound_ctrl:1
	v_add_f32_dpp v119, v119, v119 quad_perm:[1,0,3,2] row_mask:0xf bank_mask:0xf bound_ctrl:1
	s_nop 0
	ds_read_b128 v[4:7], v90 offset:0x7000
	v_add_f32_dpp v118, v118, v118 quad_perm:[2,3,0,1] row_mask:0xf bank_mask:0xf bound_ctrl:1
	s_nop 0
	ds_read_b128 v[8:11], v90 offset:0x3000
	v_add_f32_dpp v118, v118, v118 row_half_mirror row_mask:0xf bank_mask:0xf bound_ctrl:1
	s_nop 0
	ds_write2_b32 v93, v1, v119 offset0:144 offset1:180
	v_add_f32_dpp v2, v118, v118 row_mirror row_mask:0xf bank_mask:0xf bound_ctrl:1
	v_add_f32_dpp v118, v118, v118 row_mirror row_mask:0xf bank_mask:0xf bound_ctrl:1
	s_nop 0
	s_waitcnt lgkmcnt(4)
	v_permlane16_swap_b32_e32 v118, v2
	v_add_f32_e32 v118, v118, v2
	v_pk_fma_f32 v[52:53], v[102:103], v[118:119], v[54:55] op_sel_hi:[1,0,1]
	v_pk_mul_f32 v[0:1], v[52:53], v[112:113] op_sel_hi:[0,1]
	v_pk_fma_f32 v[0:1], v[52:53], v[114:115], v[0:1] op_sel:[1,0,0]
	v_pk_mul_f32 v[98:99], v[110:111], v[98:99] op_sel_hi:[0,1]
	v_pk_fma_f32 v[54:55], v[52:53], v[96:97], v[98:99]
	v_add_f32_dpp v0, v0, v0 quad_perm:[1,0,3,2] row_mask:0xf bank_mask:0xf bound_ctrl:1
	s_nop 0
	ds_read_b128 v[112:115], v90 offset:0x7200
	v_add_f32_dpp v0, v0, v0 quad_perm:[2,3,0,1] row_mask:0xf bank_mask:0xf bound_ctrl:1
	s_nop 0
	ds_read_b128 v[96:99], v90 offset:0x3200
	v_add_f32_dpp v0, v0, v0 row_half_mirror row_mask:0xf bank_mask:0xf bound_ctrl:1
	s_nop 0
	ds_read2st64_b32 v[108:109], v89 offset0:216 offset1:217
	ds_read2st64_b64 v[100:103], v88 offset0:88 offset1:89
	v_add_f32_dpp v2, v0, v0 row_mirror row_mask:0xf bank_mask:0xf bound_ctrl:1
	v_add_f32_dpp v0, v0, v0 row_mirror row_mask:0xf bank_mask:0xf bound_ctrl:1
	v_add_f32_dpp v1, v1, v1 quad_perm:[1,0,3,2] row_mask:0xf bank_mask:0xf bound_ctrl:1
	s_waitcnt lgkmcnt(7)
	v_permlane16_swap_b32_e32 v0, v2
	v_add_f32_e32 v0, v0, v2
	v_pk_fma_f32 v[52:53], v[104:105], v[0:1], v[54:55] op_sel_hi:[1,0,1]
	v_pk_mul_f32 v[118:119], v[52:53], v[120:121] op_sel_hi:[0,1]
	v_pk_fma_f32 v[118:119], v[52:53], v[122:123], v[118:119] op_sel:[1,0,0]
	v_pk_mul_f32 v[126:127], v[110:111], v[126:127] op_sel:[1,0]
	v_pk_fma_f32 v[54:55], v[52:53], v[124:125], v[126:127]
	v_add_f32_dpp v118, v118, v118 quad_perm:[1,0,3,2] row_mask:0xf bank_mask:0xf bound_ctrl:1
	v_add_f32_dpp v119, v119, v119 quad_perm:[1,0,3,2] row_mask:0xf bank_mask:0xf bound_ctrl:1
	s_nop 0
	ds_read_b128 v[120:123], v90 offset:0x7400
	v_add_f32_dpp v118, v118, v118 quad_perm:[2,3,0,1] row_mask:0xf bank_mask:0xf bound_ctrl:1
	s_nop 0
	ds_read_b128 v[124:127], v90 offset:0x3400
	v_add_f32_dpp v118, v118, v118 row_half_mirror row_mask:0xf bank_mask:0xf bound_ctrl:1
	s_nop 0
	ds_write2_b32 v93, v1, v119 offset0:216 offset1:252
	v_add_f32_dpp v2, v118, v118 row_mirror row_mask:0xf bank_mask:0xf bound_ctrl:1
	v_add_f32_dpp v118, v118, v118 row_mirror row_mask:0xf bank_mask:0xf bound_ctrl:1
	s_nop 0
	s_waitcnt lgkmcnt(4)
	v_permlane16_swap_b32_e32 v118, v2
	v_add_f32_e32 v118, v118, v2
	v_pk_fma_f32 v[52:53], v[106:107], v[118:119], v[54:55] op_sel_hi:[1,0,1]
	v_pk_mul_f32 v[0:1], v[52:53], v[4:5] op_sel_hi:[0,1]
	v_pk_fma_f32 v[0:1], v[52:53], v[6:7], v[0:1] op_sel:[1,0,0]
	v_pk_mul_f32 v[10:11], v[108:109], v[10:11] op_sel_hi:[0,1]
	v_pk_fma_f32 v[54:55], v[52:53], v[8:9], v[10:11]
	v_add_f32_dpp v0, v0, v0 quad_perm:[1,0,3,2] row_mask:0xf bank_mask:0xf bound_ctrl:1
	v_add_u32_e32 v93, 0x480, v93
	ds_read_b128 v[4:7], v90 offset:0x7600
	v_add_f32_dpp v0, v0, v0 quad_perm:[2,3,0,1] row_mask:0xf bank_mask:0xf bound_ctrl:1
	s_nop 0
	ds_read_b128 v[8:11], v90 offset:0x3600
	v_add_f32_dpp v0, v0, v0 row_half_mirror row_mask:0xf bank_mask:0xf bound_ctrl:1
	s_nop 0
	ds_read2st64_b32 v[110:111], v89 offset0:218 offset1:219
	ds_read2st64_b64 v[104:107], v88 offset0:90 offset1:91
	v_add_f32_dpp v2, v0, v0 row_mirror row_mask:0xf bank_mask:0xf bound_ctrl:1
	v_add_f32_dpp v0, v0, v0 row_mirror row_mask:0xf bank_mask:0xf bound_ctrl:1
	v_add_f32_dpp v1, v1, v1 quad_perm:[1,0,3,2] row_mask:0xf bank_mask:0xf bound_ctrl:1
	s_waitcnt lgkmcnt(7)
	v_permlane16_swap_b32_e32 v0, v2
	v_add_f32_e32 v0, v0, v2
	v_pk_fma_f32 v[52:53], v[100:101], v[0:1], v[54:55] op_sel_hi:[1,0,1]
	v_pk_mul_f32 v[118:119], v[52:53], v[112:113] op_sel_hi:[0,1]
	v_pk_fma_f32 v[118:119], v[52:53], v[114:115], v[118:119] op_sel:[1,0,0]
	v_pk_mul_f32 v[98:99], v[108:109], v[98:99] op_sel:[1,0]
	v_pk_fma_f32 v[54:55], v[52:53], v[96:97], v[98:99]
	v_add_f32_dpp v118, v118, v118 quad_perm:[1,0,3,2] row_mask:0xf bank_mask:0xf bound_ctrl:1
	v_add_f32_dpp v119, v119, v119 quad_perm:[1,0,3,2] row_mask:0xf bank_mask:0xf bound_ctrl:1
	s_nop 0
	ds_read_b128 v[112:115], v90 offset:0x7800
	v_add_f32_dpp v118, v118, v118 quad_perm:[2,3,0,1] row_mask:0xf bank_mask:0xf bound_ctrl:1
	s_nop 0
	ds_read_b128 v[96:99], v90 offset:0x3800
	v_add_f32_dpp v118, v118, v118 row_half_mirror row_mask:0xf bank_mask:0xf bound_ctrl:1
	s_nop 0
	ds_write2_b32 v93, v1, v119 offset0:0 offset1:36
	v_add_f32_dpp v2, v118, v118 row_mirror row_mask:0xf bank_mask:0xf bound_ctrl:1
	v_add_f32_dpp v118, v118, v118 row_mirror row_mask:0xf bank_mask:0xf bound_ctrl:1
	s_nop 0
	s_waitcnt lgkmcnt(4)
	v_permlane16_swap_b32_e32 v118, v2
	v_add_f32_e32 v118, v118, v2
	v_pk_fma_f32 v[52:53], v[102:103], v[118:119], v[54:55] op_sel_hi:[1,0,1]
	v_pk_mul_f32 v[0:1], v[52:53], v[120:121] op_sel_hi:[0,1]
	v_pk_fma_f32 v[0:1], v[52:53], v[122:123], v[0:1] op_sel:[1,0,0]
	v_pk_mul_f32 v[126:127], v[110:111], v[126:127] op_sel_hi:[0,1]
	v_pk_fma_f32 v[54:55], v[52:53], v[124:125], v[126:127]
	v_add_f32_dpp v0, v0, v0 quad_perm:[1,0,3,2] row_mask:0xf bank_mask:0xf bound_ctrl:1
	s_nop 0
	ds_read_b128 v[120:123], v90 offset:0x7a00
	v_add_f32_dpp v0, v0, v0 quad_perm:[2,3,0,1] row_mask:0xf bank_mask:0xf bound_ctrl:1
	s_nop 0
	ds_read_b128 v[124:127], v90 offset:0x3a00
	v_add_f32_dpp v0, v0, v0 row_half_mirror row_mask:0xf bank_mask:0xf bound_ctrl:1
	s_nop 0
	ds_read2st64_b32 v[108:109], v89 offset0:220 offset1:221
	ds_read2st64_b64 v[100:103], v88 offset0:92 offset1:93
	v_add_f32_dpp v2, v0, v0 row_mirror row_mask:0xf bank_mask:0xf bound_ctrl:1
	v_add_f32_dpp v0, v0, v0 row_mirror row_mask:0xf bank_mask:0xf bound_ctrl:1
	v_add_f32_dpp v1, v1, v1 quad_perm:[1,0,3,2] row_mask:0xf bank_mask:0xf bound_ctrl:1
	s_waitcnt lgkmcnt(7)
	v_permlane16_swap_b32_e32 v0, v2
	v_add_f32_e32 v0, v0, v2
	v_pk_fma_f32 v[52:53], v[104:105], v[0:1], v[54:55] op_sel_hi:[1,0,1]
	v_pk_mul_f32 v[118:119], v[52:53], v[4:5] op_sel_hi:[0,1]
	v_pk_fma_f32 v[118:119], v[52:53], v[6:7], v[118:119] op_sel:[1,0,0]
	v_pk_mul_f32 v[10:11], v[110:111], v[10:11] op_sel:[1,0]
	v_pk_fma_f32 v[54:55], v[52:53], v[8:9], v[10:11]
	v_add_f32_dpp v118, v118, v118 quad_perm:[1,0,3,2] row_mask:0xf bank_mask:0xf bound_ctrl:1
	v_add_f32_dpp v119, v119, v119 quad_perm:[1,0,3,2] row_mask:0xf bank_mask:0xf bound_ctrl:1
	s_nop 0
	ds_read_b128 v[4:7], v90 offset:0x7c00
	v_add_f32_dpp v118, v118, v118 quad_perm:[2,3,0,1] row_mask:0xf bank_mask:0xf bound_ctrl:1
	s_nop 0
	ds_read_b128 v[8:11], v90 offset:0x3c00
	v_add_f32_dpp v118, v118, v118 row_half_mirror row_mask:0xf bank_mask:0xf bound_ctrl:1
	s_nop 0
	ds_write2_b32 v93, v1, v119 offset0:72 offset1:108
	v_add_f32_dpp v2, v118, v118 row_mirror row_mask:0xf bank_mask:0xf bound_ctrl:1
	v_add_f32_dpp v118, v118, v118 row_mirror row_mask:0xf bank_mask:0xf bound_ctrl:1
	s_nop 0
	s_waitcnt lgkmcnt(4)
	v_permlane16_swap_b32_e32 v118, v2
	v_add_f32_e32 v118, v118, v2
	v_pk_fma_f32 v[52:53], v[106:107], v[118:119], v[54:55] op_sel_hi:[1,0,1]
	v_pk_mul_f32 v[0:1], v[52:53], v[112:113] op_sel_hi:[0,1]
	v_pk_fma_f32 v[0:1], v[52:53], v[114:115], v[0:1] op_sel:[1,0,0]
	v_pk_mul_f32 v[98:99], v[108:109], v[98:99] op_sel_hi:[0,1]
	v_pk_fma_f32 v[54:55], v[52:53], v[96:97], v[98:99]
	v_add_f32_dpp v0, v0, v0 quad_perm:[1,0,3,2] row_mask:0xf bank_mask:0xf bound_ctrl:1
	s_nop 0
	ds_read_b128 v[112:115], v90 offset:0x7e00
	v_add_f32_dpp v0, v0, v0 quad_perm:[2,3,0,1] row_mask:0xf bank_mask:0xf bound_ctrl:1
	s_nop 0
	ds_read_b128 v[96:99], v90 offset:0x3e00
	v_add_f32_dpp v0, v0, v0 row_half_mirror row_mask:0xf bank_mask:0xf bound_ctrl:1
	s_nop 0
	ds_read2st64_b32 v[110:111], v89 offset0:222 offset1:223
	ds_read2st64_b64 v[104:107], v88 offset0:94 offset1:95
	v_add_f32_dpp v2, v0, v0 row_mirror row_mask:0xf bank_mask:0xf bound_ctrl:1
	v_add_f32_dpp v0, v0, v0 row_mirror row_mask:0xf bank_mask:0xf bound_ctrl:1
	v_add_f32_dpp v1, v1, v1 quad_perm:[1,0,3,2] row_mask:0xf bank_mask:0xf bound_ctrl:1
	s_waitcnt lgkmcnt(7)
	v_permlane16_swap_b32_e32 v0, v2
	v_add_f32_e32 v0, v0, v2
	v_pk_fma_f32 v[52:53], v[100:101], v[0:1], v[54:55] op_sel_hi:[1,0,1]
	v_pk_mul_f32 v[118:119], v[52:53], v[120:121] op_sel_hi:[0,1]
	v_pk_fma_f32 v[118:119], v[52:53], v[122:123], v[118:119] op_sel:[1,0,0]
	v_pk_mul_f32 v[126:127], v[108:109], v[126:127] op_sel:[1,0]
	v_pk_fma_f32 v[54:55], v[52:53], v[124:125], v[126:127]
	v_add_f32_dpp v118, v118, v118 quad_perm:[1,0,3,2] row_mask:0xf bank_mask:0xf bound_ctrl:1
	v_add_f32_dpp v119, v119, v119 quad_perm:[1,0,3,2] row_mask:0xf bank_mask:0xf bound_ctrl:1
	s_nop 0
	s_nop 0
	v_add_f32_dpp v118, v118, v118 quad_perm:[2,3,0,1] row_mask:0xf bank_mask:0xf bound_ctrl:1
	s_nop 0
	s_nop 0
	v_add_f32_dpp v118, v118, v118 row_half_mirror row_mask:0xf bank_mask:0xf bound_ctrl:1
	s_nop 0
	ds_write2_b32 v93, v1, v119 offset0:144 offset1:180
	v_add_f32_dpp v2, v118, v118 row_mirror row_mask:0xf bank_mask:0xf bound_ctrl:1
	v_add_f32_dpp v118, v118, v118 row_mirror row_mask:0xf bank_mask:0xf bound_ctrl:1
	s_nop 0
	s_waitcnt lgkmcnt(2)
	v_permlane16_swap_b32_e32 v118, v2
	v_add_f32_e32 v118, v118, v2
	v_pk_fma_f32 v[52:53], v[102:103], v[118:119], v[54:55] op_sel_hi:[1,0,1]
	v_pk_mul_f32 v[0:1], v[52:53], v[4:5] op_sel_hi:[0,1]
	v_pk_fma_f32 v[0:1], v[52:53], v[6:7], v[0:1] op_sel:[1,0,0]
	v_pk_mul_f32 v[10:11], v[110:111], v[10:11] op_sel_hi:[0,1]
	v_pk_fma_f32 v[54:55], v[52:53], v[8:9], v[10:11]
	v_add_f32_dpp v0, v0, v0 quad_perm:[1,0,3,2] row_mask:0xf bank_mask:0xf bound_ctrl:1
	s_nop 0
	s_nop 0
	v_add_f32_dpp v0, v0, v0 quad_perm:[2,3,0,1] row_mask:0xf bank_mask:0xf bound_ctrl:1
	s_nop 0
	s_nop 0
	v_add_f32_dpp v0, v0, v0 row_half_mirror row_mask:0xf bank_mask:0xf bound_ctrl:1
	s_nop 0
	s_nop 0
	v_add_f32_dpp v2, v0, v0 row_mirror row_mask:0xf bank_mask:0xf bound_ctrl:1
	v_add_f32_dpp v0, v0, v0 row_mirror row_mask:0xf bank_mask:0xf bound_ctrl:1
	v_add_f32_dpp v1, v1, v1 quad_perm:[1,0,3,2] row_mask:0xf bank_mask:0xf bound_ctrl:1
	s_waitcnt lgkmcnt(1)
	v_permlane16_swap_b32_e32 v0, v2
	v_add_f32_e32 v0, v0, v2
	v_pk_fma_f32 v[52:53], v[104:105], v[0:1], v[54:55] op_sel_hi:[1,0,1]
	v_pk_mul_f32 v[118:119], v[52:53], v[112:113] op_sel_hi:[0,1]
	v_pk_fma_f32 v[118:119], v[52:53], v[114:115], v[118:119] op_sel:[1,0,0]
	v_pk_mul_f32 v[98:99], v[110:111], v[98:99] op_sel:[1,0]
	v_pk_fma_f32 v[54:55], v[52:53], v[96:97], v[98:99]
	v_add_f32_dpp v118, v118, v118 quad_perm:[1,0,3,2] row_mask:0xf bank_mask:0xf bound_ctrl:1
	v_add_f32_dpp v119, v119, v119 quad_perm:[1,0,3,2] row_mask:0xf bank_mask:0xf bound_ctrl:1
	s_nop 0
	s_nop 0
	v_add_f32_dpp v118, v118, v118 quad_perm:[2,3,0,1] row_mask:0xf bank_mask:0xf bound_ctrl:1
	s_nop 0
	s_nop 0
	v_add_f32_dpp v118, v118, v118 row_half_mirror row_mask:0xf bank_mask:0xf bound_ctrl:1
	s_nop 0
	ds_write2_b32 v93, v1, v119 offset0:216 offset1:252
	v_add_f32_dpp v2, v118, v118 row_mirror row_mask:0xf bank_mask:0xf bound_ctrl:1
	v_add_f32_dpp v118, v118, v118 row_mirror row_mask:0xf bank_mask:0xf bound_ctrl:1
	s_nop 0
	s_nop 0
	v_permlane16_swap_b32_e32 v118, v2
	v_add_f32_e32 v118, v118, v2
	v_pk_fma_f32 v[52:53], v[106:107], v[118:119], v[54:55] op_sel_hi:[1,0,1]
